# write-through (sc0 sc1) stores also on the remaining main-GEMM epilogue paths (gelu / KV tiles)
# baseline (speedup 1.0000x reference)
.Lmain_kv:
	s_bitcmp1_b32 s6, 1
	s_cbranch_scc0 .Lmain_old
	s_cmp_ge_u32 s6, 4
	s_cbranch_scc0 .Lmain_old
	s_mov_b32 s20, 0xcccccccc
	s_mov_b32 s21, 0xcccccccc
	s_mov_b32 s24, 0xf0f0f0f0
	s_mov_b32 s25, 0xf0f0f0f0
	s_mov_b32 s22, 0xaaaaaaaa
	s_mov_b32 s23, 0xaaaaaaaa
	v_mov_b32_e32 v216, 0x5040100
	v_mov_b32_e32 v152, 0x3020706
	v_cndmask_b32_e64 v216, v216, v152, s[22:23]
	v_and_b32_e32 v152, 1, v166
	v_and_b32_e32 v153, 4, v166
	v_lshrrev_b32_e32 v153, 1, v153
	v_and_b32_e32 v154, 2, v166
	v_lshlrev_b32_e32 v154, 1, v154
	v_or3_b32 v152, v152, v153, v154
	v_lshlrev_b32_e32 v217, 4, v152
	v_lshl_add_u32 v217, v32, 3, v217
	v_lshrrev_b32_e32 v153, 3, v166
	v_lshl_add_u32 v217, v153, 11, v217
	s_lshl_b32 s7, s45, 8
	v_add_u32_e32 v217, s7, v217
	s_lshr_b32 s7, s6, 1
	s_lshl_b32 s7, s7, 24
	s_add_u32 s22, s76, s7
	s_addc_u32 s23, s77, 0
	s_add_u32 s22, s22, 0x31e51000
	s_addc_u32 s23, s23, 0
	s_lshr_b32 s7, s31, 3
	s_lshl_b32 s7, s7, 2
	s_and_b32 s13, s6, 1
	s_lshl_b32 s13, s13, 1
	s_add_i32 s7, s7, s13
	s_lshl_b32 s7, s7, 19
	s_and_b32 s13, s31, 7
	s_lshl_b32 s13, s13, 16
	s_add_i32 s7, s7, s13
	s_add_u32 s22, s22, s7
	s_addc_u32 s23, s23, 0
	s_add_u32 s10, s22, 0
	s_addc_u32 s11, s23, 0
	v_cvt_pk_bf16_f32 v148, v126, v127
	v_cvt_pk_bf16_f32 v149, v128, v129
	v_cvt_pk_bf16_f32 v150, v122, v123
	v_cvt_pk_bf16_f32 v151, v124, v125
	s_nop 1
	v_mov_b32_dpp v152, v148 quad_perm:[1,0,3,2] row_mask:0xf bank_mask:0xf
	v_mov_b32_dpp v153, v149 quad_perm:[1,0,3,2] row_mask:0xf bank_mask:0xf
	v_mov_b32_dpp v154, v150 quad_perm:[1,0,3,2] row_mask:0xf bank_mask:0xf
	v_mov_b32_dpp v155, v151 quad_perm:[1,0,3,2] row_mask:0xf bank_mask:0xf
	v_perm_b32 v148, v152, v148, v216
	v_perm_b32 v149, v153, v149, v216
	v_perm_b32 v150, v154, v150, v216
	v_perm_b32 v151, v155, v151, v216
	v_cndmask_b32_e64 v160, v150, v148, s[20:21]
	v_cndmask_b32_e64 v161, v151, v149, s[20:21]
	s_nop 1
	v_mov_b32_dpp v162, v160 quad_perm:[2,3,0,1] row_mask:0xf bank_mask:0xf
	v_mov_b32_dpp v163, v161 quad_perm:[2,3,0,1] row_mask:0xf bank_mask:0xf
	v_cndmask_b32_e64 v156, v148, v162, s[20:21]
	v_cndmask_b32_e64 v157, v162, v150, s[20:21]
	v_cndmask_b32_e64 v158, v149, v163, s[20:21]
	v_cndmask_b32_e64 v159, v163, v151, s[20:21]
	v_cndmask_b32_e64 v160, v158, v156, s[24:25]
	v_cndmask_b32_e64 v161, v159, v157, s[24:25]
	s_nop 1
	v_mov_b32_dpp v162, v160 row_shl:4 row_mask:0xf bank_mask:0x5
	v_mov_b32_dpp v163, v161 row_shl:4 row_mask:0xf bank_mask:0x5
	v_mov_b32_dpp v162, v160 row_shr:4 row_mask:0xf bank_mask:0xa
	v_mov_b32_dpp v163, v161 row_shr:4 row_mask:0xf bank_mask:0xa
	v_cndmask_b32_e64 v208, v156, v162, s[24:25]
	v_cndmask_b32_e64 v209, v157, v163, s[24:25]
	v_cndmask_b32_e64 v210, v162, v158, s[24:25]
	v_cndmask_b32_e64 v211, v163, v159, s[24:25]
	global_store_dwordx4 v217, v[208:211], s[10:11] sc0 sc1
	s_add_u32 s10, s22, 0x80000
	s_addc_u32 s11, s23, 0
	v_cvt_pk_bf16_f32 v148, v118, v119
	v_cvt_pk_bf16_f32 v149, v120, v121
	v_cvt_pk_bf16_f32 v150, v114, v115
	v_cvt_pk_bf16_f32 v151, v116, v117
	s_nop 1
	v_mov_b32_dpp v152, v148 quad_perm:[1,0,3,2] row_mask:0xf bank_mask:0xf
	v_mov_b32_dpp v153, v149 quad_perm:[1,0,3,2] row_mask:0xf bank_mask:0xf
	v_mov_b32_dpp v154, v150 quad_perm:[1,0,3,2] row_mask:0xf bank_mask:0xf
	v_mov_b32_dpp v155, v151 quad_perm:[1,0,3,2] row_mask:0xf bank_mask:0xf
	v_perm_b32 v148, v152, v148, v216
	v_perm_b32 v149, v153, v149, v216
	v_perm_b32 v150, v154, v150, v216
	v_perm_b32 v151, v155, v151, v216
	v_cndmask_b32_e64 v160, v150, v148, s[20:21]
	v_cndmask_b32_e64 v161, v151, v149, s[20:21]
	s_nop 1
	v_mov_b32_dpp v162, v160 quad_perm:[2,3,0,1] row_mask:0xf bank_mask:0xf
	v_mov_b32_dpp v163, v161 quad_perm:[2,3,0,1] row_mask:0xf bank_mask:0xf
	v_cndmask_b32_e64 v156, v148, v162, s[20:21]
	v_cndmask_b32_e64 v157, v162, v150, s[20:21]
	v_cndmask_b32_e64 v158, v149, v163, s[20:21]
	v_cndmask_b32_e64 v159, v163, v151, s[20:21]
	v_cndmask_b32_e64 v160, v158, v156, s[24:25]
	v_cndmask_b32_e64 v161, v159, v157, s[24:25]
	s_nop 1
	v_mov_b32_dpp v162, v160 row_shl:4 row_mask:0xf bank_mask:0x5
	v_mov_b32_dpp v163, v161 row_shl:4 row_mask:0xf bank_mask:0x5
	v_mov_b32_dpp v162, v160 row_shr:4 row_mask:0xf bank_mask:0xa
	v_mov_b32_dpp v163, v161 row_shr:4 row_mask:0xf bank_mask:0xa
	v_cndmask_b32_e64 v212, v156, v162, s[24:25]
	v_cndmask_b32_e64 v213, v157, v163, s[24:25]
	v_cndmask_b32_e64 v214, v162, v158, s[24:25]
	v_cndmask_b32_e64 v215, v163, v159, s[24:25]
	global_store_dwordx4 v217, v[212:215], s[10:11] sc0 sc1
	s_add_u32 s10, s22, 0x1000
	s_addc_u32 s11, s23, 0
	v_cvt_pk_bf16_f32 v148, v110, v111
	v_cvt_pk_bf16_f32 v149, v112, v113
	v_cvt_pk_bf16_f32 v150, v106, v107
	v_cvt_pk_bf16_f32 v151, v108, v109
	s_nop 1
	v_mov_b32_dpp v152, v148 quad_perm:[1,0,3,2] row_mask:0xf bank_mask:0xf
	v_mov_b32_dpp v153, v149 quad_perm:[1,0,3,2] row_mask:0xf bank_mask:0xf
	v_mov_b32_dpp v154, v150 quad_perm:[1,0,3,2] row_mask:0xf bank_mask:0xf
	v_mov_b32_dpp v155, v151 quad_perm:[1,0,3,2] row_mask:0xf bank_mask:0xf
	v_perm_b32 v148, v152, v148, v216
	v_perm_b32 v149, v153, v149, v216
	v_perm_b32 v150, v154, v150, v216
	v_perm_b32 v151, v155, v151, v216
	v_cndmask_b32_e64 v160, v150, v148, s[20:21]
	v_cndmask_b32_e64 v161, v151, v149, s[20:21]
	s_nop 1
	v_mov_b32_dpp v162, v160 quad_perm:[2,3,0,1] row_mask:0xf bank_mask:0xf
	v_mov_b32_dpp v163, v161 quad_perm:[2,3,0,1] row_mask:0xf bank_mask:0xf
	v_cndmask_b32_e64 v156, v148, v162, s[20:21]
	v_cndmask_b32_e64 v157, v162, v150, s[20:21]
	v_cndmask_b32_e64 v158, v149, v163, s[20:21]
	v_cndmask_b32_e64 v159, v163, v151, s[20:21]
	v_cndmask_b32_e64 v160, v158, v156, s[24:25]
	v_cndmask_b32_e64 v161, v159, v157, s[24:25]
	s_nop 1
	v_mov_b32_dpp v162, v160 row_shl:4 row_mask:0xf bank_mask:0x5
	v_mov_b32_dpp v163, v161 row_shl:4 row_mask:0xf bank_mask:0x5
	v_mov_b32_dpp v162, v160 row_shr:4 row_mask:0xf bank_mask:0xa
	v_mov_b32_dpp v163, v161 row_shr:4 row_mask:0xf bank_mask:0xa
	v_cndmask_b32_e64 v208, v156, v162, s[24:25]
	v_cndmask_b32_e64 v209, v157, v163, s[24:25]
	v_cndmask_b32_e64 v210, v162, v158, s[24:25]
	v_cndmask_b32_e64 v211, v163, v159, s[24:25]
	global_store_dwordx4 v217, v[208:211], s[10:11] sc0 sc1
	s_add_u32 s10, s22, 0x81000
	s_addc_u32 s11, s23, 0
	v_cvt_pk_bf16_f32 v148, v102, v103
	v_cvt_pk_bf16_f32 v149, v104, v105
	v_cvt_pk_bf16_f32 v150, v98, v99
	v_cvt_pk_bf16_f32 v151, v100, v101
	s_nop 1
	v_mov_b32_dpp v152, v148 quad_perm:[1,0,3,2] row_mask:0xf bank_mask:0xf
	v_mov_b32_dpp v153, v149 quad_perm:[1,0,3,2] row_mask:0xf bank_mask:0xf
	v_mov_b32_dpp v154, v150 quad_perm:[1,0,3,2] row_mask:0xf bank_mask:0xf
	v_mov_b32_dpp v155, v151 quad_perm:[1,0,3,2] row_mask:0xf bank_mask:0xf
	v_perm_b32 v148, v152, v148, v216
	v_perm_b32 v149, v153, v149, v216
	v_perm_b32 v150, v154, v150, v216
	v_perm_b32 v151, v155, v151, v216
	v_cndmask_b32_e64 v160, v150, v148, s[20:21]
	v_cndmask_b32_e64 v161, v151, v149, s[20:21]
	s_nop 1
	v_mov_b32_dpp v162, v160 quad_perm:[2,3,0,1] row_mask:0xf bank_mask:0xf
	v_mov_b32_dpp v163, v161 quad_perm:[2,3,0,1] row_mask:0xf bank_mask:0xf
	v_cndmask_b32_e64 v156, v148, v162, s[20:21]
	v_cndmask_b32_e64 v157, v162, v150, s[20:21]
	v_cndmask_b32_e64 v158, v149, v163, s[20:21]
	v_cndmask_b32_e64 v159, v163, v151, s[20:21]
	v_cndmask_b32_e64 v160, v158, v156, s[24:25]
	v_cndmask_b32_e64 v161, v159, v157, s[24:25]
	s_nop 1
	v_mov_b32_dpp v162, v160 row_shl:4 row_mask:0xf bank_mask:0x5
	v_mov_b32_dpp v163, v161 row_shl:4 row_mask:0xf bank_mask:0x5
	v_mov_b32_dpp v162, v160 row_shr:4 row_mask:0xf bank_mask:0xa
	v_mov_b32_dpp v163, v161 row_shr:4 row_mask:0xf bank_mask:0xa
	v_cndmask_b32_e64 v212, v156, v162, s[24:25]
	v_cndmask_b32_e64 v213, v157, v163, s[24:25]
	v_cndmask_b32_e64 v214, v162, v158, s[24:25]
	v_cndmask_b32_e64 v215, v163, v159, s[24:25]
	global_store_dwordx4 v217, v[212:215], s[10:11] sc0 sc1
	s_add_u32 s10, s22, 0x2000
	s_addc_u32 s11, s23, 0
	v_cvt_pk_bf16_f32 v148, v94, v95
	v_cvt_pk_bf16_f32 v149, v96, v97
	v_cvt_pk_bf16_f32 v150, v90, v91
	v_cvt_pk_bf16_f32 v151, v92, v93
	s_nop 1
	v_mov_b32_dpp v152, v148 quad_perm:[1,0,3,2] row_mask:0xf bank_mask:0xf
	v_mov_b32_dpp v153, v149 quad_perm:[1,0,3,2] row_mask:0xf bank_mask:0xf
	v_mov_b32_dpp v154, v150 quad_perm:[1,0,3,2] row_mask:0xf bank_mask:0xf
	v_mov_b32_dpp v155, v151 quad_perm:[1,0,3,2] row_mask:0xf bank_mask:0xf
	v_perm_b32 v148, v152, v148, v216
	v_perm_b32 v149, v153, v149, v216
	v_perm_b32 v150, v154, v150, v216
	v_perm_b32 v151, v155, v151, v216
	v_cndmask_b32_e64 v160, v150, v148, s[20:21]
	v_cndmask_b32_e64 v161, v151, v149, s[20:21]
	s_nop 1
	v_mov_b32_dpp v162, v160 quad_perm:[2,3,0,1] row_mask:0xf bank_mask:0xf
	v_mov_b32_dpp v163, v161 quad_perm:[2,3,0,1] row_mask:0xf bank_mask:0xf
	v_cndmask_b32_e64 v156, v148, v162, s[20:21]
	v_cndmask_b32_e64 v157, v162, v150, s[20:21]
	v_cndmask_b32_e64 v158, v149, v163, s[20:21]
	v_cndmask_b32_e64 v159, v163, v151, s[20:21]
	v_cndmask_b32_e64 v160, v158, v156, s[24:25]
	v_cndmask_b32_e64 v161, v159, v157, s[24:25]
	s_nop 1
	v_mov_b32_dpp v162, v160 row_shl:4 row_mask:0xf bank_mask:0x5
	v_mov_b32_dpp v163, v161 row_shl:4 row_mask:0xf bank_mask:0x5
	v_mov_b32_dpp v162, v160 row_shr:4 row_mask:0xf bank_mask:0xa
	v_mov_b32_dpp v163, v161 row_shr:4 row_mask:0xf bank_mask:0xa
	v_cndmask_b32_e64 v208, v156, v162, s[24:25]
	v_cndmask_b32_e64 v209, v157, v163, s[24:25]
	v_cndmask_b32_e64 v210, v162, v158, s[24:25]
	v_cndmask_b32_e64 v211, v163, v159, s[24:25]
	global_store_dwordx4 v217, v[208:211], s[10:11] sc0 sc1
	s_add_u32 s10, s22, 0x82000
	s_addc_u32 s11, s23, 0
	v_cvt_pk_bf16_f32 v148, v86, v87
	v_cvt_pk_bf16_f32 v149, v88, v89
	v_cvt_pk_bf16_f32 v150, v82, v83
	v_cvt_pk_bf16_f32 v151, v84, v85
	s_nop 1
	v_mov_b32_dpp v152, v148 quad_perm:[1,0,3,2] row_mask:0xf bank_mask:0xf
	v_mov_b32_dpp v153, v149 quad_perm:[1,0,3,2] row_mask:0xf bank_mask:0xf
	v_mov_b32_dpp v154, v150 quad_perm:[1,0,3,2] row_mask:0xf bank_mask:0xf
	v_mov_b32_dpp v155, v151 quad_perm:[1,0,3,2] row_mask:0xf bank_mask:0xf
	v_perm_b32 v148, v152, v148, v216
	v_perm_b32 v149, v153, v149, v216
	v_perm_b32 v150, v154, v150, v216
	v_perm_b32 v151, v155, v151, v216
	v_cndmask_b32_e64 v160, v150, v148, s[20:21]
	v_cndmask_b32_e64 v161, v151, v149, s[20:21]
	s_nop 1
	v_mov_b32_dpp v162, v160 quad_perm:[2,3,0,1] row_mask:0xf bank_mask:0xf
	v_mov_b32_dpp v163, v161 quad_perm:[2,3,0,1] row_mask:0xf bank_mask:0xf
	v_cndmask_b32_e64 v156, v148, v162, s[20:21]
	v_cndmask_b32_e64 v157, v162, v150, s[20:21]
	v_cndmask_b32_e64 v158, v149, v163, s[20:21]
	v_cndmask_b32_e64 v159, v163, v151, s[20:21]
	v_cndmask_b32_e64 v160, v158, v156, s[24:25]
	v_cndmask_b32_e64 v161, v159, v157, s[24:25]
	s_nop 1
	v_mov_b32_dpp v162, v160 row_shl:4 row_mask:0xf bank_mask:0x5
	v_mov_b32_dpp v163, v161 row_shl:4 row_mask:0xf bank_mask:0x5
	v_mov_b32_dpp v162, v160 row_shr:4 row_mask:0xf bank_mask:0xa
	v_mov_b32_dpp v163, v161 row_shr:4 row_mask:0xf bank_mask:0xa
	v_cndmask_b32_e64 v212, v156, v162, s[24:25]
	v_cndmask_b32_e64 v213, v157, v163, s[24:25]
	v_cndmask_b32_e64 v214, v162, v158, s[24:25]
	v_cndmask_b32_e64 v215, v163, v159, s[24:25]
	global_store_dwordx4 v217, v[212:215], s[10:11] sc0 sc1
	s_add_u32 s10, s22, 0x3000
	s_addc_u32 s11, s23, 0
	v_cvt_pk_bf16_f32 v148, v78, v79
	v_cvt_pk_bf16_f32 v149, v80, v81
	v_cvt_pk_bf16_f32 v150, v74, v75
	v_cvt_pk_bf16_f32 v151, v76, v77
	s_nop 1
	v_mov_b32_dpp v152, v148 quad_perm:[1,0,3,2] row_mask:0xf bank_mask:0xf
	v_mov_b32_dpp v153, v149 quad_perm:[1,0,3,2] row_mask:0xf bank_mask:0xf
	v_mov_b32_dpp v154, v150 quad_perm:[1,0,3,2] row_mask:0xf bank_mask:0xf
	v_mov_b32_dpp v155, v151 quad_perm:[1,0,3,2] row_mask:0xf bank_mask:0xf
	v_perm_b32 v148, v152, v148, v216
	v_perm_b32 v149, v153, v149, v216
	v_perm_b32 v150, v154, v150, v216
	v_perm_b32 v151, v155, v151, v216
	v_cndmask_b32_e64 v160, v150, v148, s[20:21]
	v_cndmask_b32_e64 v161, v151, v149, s[20:21]
	s_nop 1
	v_mov_b32_dpp v162, v160 quad_perm:[2,3,0,1] row_mask:0xf bank_mask:0xf
	v_mov_b32_dpp v163, v161 quad_perm:[2,3,0,1] row_mask:0xf bank_mask:0xf
	v_cndmask_b32_e64 v156, v148, v162, s[20:21]
	v_cndmask_b32_e64 v157, v162, v150, s[20:21]
	v_cndmask_b32_e64 v158, v149, v163, s[20:21]
	v_cndmask_b32_e64 v159, v163, v151, s[20:21]
	v_cndmask_b32_e64 v160, v158, v156, s[24:25]
	v_cndmask_b32_e64 v161, v159, v157, s[24:25]
	s_nop 1
	v_mov_b32_dpp v162, v160 row_shl:4 row_mask:0xf bank_mask:0x5
	v_mov_b32_dpp v163, v161 row_shl:4 row_mask:0xf bank_mask:0x5
	v_mov_b32_dpp v162, v160 row_shr:4 row_mask:0xf bank_mask:0xa
	v_mov_b32_dpp v163, v161 row_shr:4 row_mask:0xf bank_mask:0xa
	v_cndmask_b32_e64 v208, v156, v162, s[24:25]
	v_cndmask_b32_e64 v209, v157, v163, s[24:25]
	v_cndmask_b32_e64 v210, v162, v158, s[24:25]
	v_cndmask_b32_e64 v211, v163, v159, s[24:25]
	global_store_dwordx4 v217, v[208:211], s[10:11] sc0 sc1
	s_add_u32 s10, s22, 0x83000
	s_addc_u32 s11, s23, 0
	v_cvt_pk_bf16_f32 v148, v70, v71
	v_cvt_pk_bf16_f32 v149, v72, v73
	v_cvt_pk_bf16_f32 v150, v66, v67
	v_cvt_pk_bf16_f32 v151, v68, v69
	s_nop 1
	v_mov_b32_dpp v152, v148 quad_perm:[1,0,3,2] row_mask:0xf bank_mask:0xf
	v_mov_b32_dpp v153, v149 quad_perm:[1,0,3,2] row_mask:0xf bank_mask:0xf
	v_mov_b32_dpp v154, v150 quad_perm:[1,0,3,2] row_mask:0xf bank_mask:0xf
	v_mov_b32_dpp v155, v151 quad_perm:[1,0,3,2] row_mask:0xf bank_mask:0xf
	v_perm_b32 v148, v152, v148, v216
	v_perm_b32 v149, v153, v149, v216
	v_perm_b32 v150, v154, v150, v216
	v_perm_b32 v151, v155, v151, v216
	v_cndmask_b32_e64 v160, v150, v148, s[20:21]
	v_cndmask_b32_e64 v161, v151, v149, s[20:21]
	s_nop 1
	v_mov_b32_dpp v162, v160 quad_perm:[2,3,0,1] row_mask:0xf bank_mask:0xf
	v_mov_b32_dpp v163, v161 quad_perm:[2,3,0,1] row_mask:0xf bank_mask:0xf
	v_cndmask_b32_e64 v156, v148, v162, s[20:21]
	v_cndmask_b32_e64 v157, v162, v150, s[20:21]
	v_cndmask_b32_e64 v158, v149, v163, s[20:21]
	v_cndmask_b32_e64 v159, v163, v151, s[20:21]
	v_cndmask_b32_e64 v160, v158, v156, s[24:25]
	v_cndmask_b32_e64 v161, v159, v157, s[24:25]
	s_nop 1
	v_mov_b32_dpp v162, v160 row_shl:4 row_mask:0xf bank_mask:0x5
	v_mov_b32_dpp v163, v161 row_shl:4 row_mask:0xf bank_mask:0x5
	v_mov_b32_dpp v162, v160 row_shr:4 row_mask:0xf bank_mask:0xa
	v_mov_b32_dpp v163, v161 row_shr:4 row_mask:0xf bank_mask:0xa
	v_cndmask_b32_e64 v212, v156, v162, s[24:25]
	v_cndmask_b32_e64 v213, v157, v163, s[24:25]
	v_cndmask_b32_e64 v214, v162, v158, s[24:25]
	v_cndmask_b32_e64 v215, v163, v159, s[24:25]
	global_store_dwordx4 v217, v[212:215], s[10:11] sc0 sc1
	s_add_u32 s10, s22, 0x8000
	s_addc_u32 s11, s23, 0
	v_cvt_pk_bf16_f32 v148, v62, v63
	v_cvt_pk_bf16_f32 v149, v64, v65
	v_cvt_pk_bf16_f32 v150, v58, v59
	v_cvt_pk_bf16_f32 v151, v60, v61
	s_nop 1
	v_mov_b32_dpp v152, v148 quad_perm:[1,0,3,2] row_mask:0xf bank_mask:0xf
	v_mov_b32_dpp v153, v149 quad_perm:[1,0,3,2] row_mask:0xf bank_mask:0xf
	v_mov_b32_dpp v154, v150 quad_perm:[1,0,3,2] row_mask:0xf bank_mask:0xf
	v_mov_b32_dpp v155, v151 quad_perm:[1,0,3,2] row_mask:0xf bank_mask:0xf
	v_perm_b32 v148, v152, v148, v216
	v_perm_b32 v149, v153, v149, v216
	v_perm_b32 v150, v154, v150, v216
	v_perm_b32 v151, v155, v151, v216
	v_cndmask_b32_e64 v160, v150, v148, s[20:21]
	v_cndmask_b32_e64 v161, v151, v149, s[20:21]
	s_nop 1
	v_mov_b32_dpp v162, v160 quad_perm:[2,3,0,1] row_mask:0xf bank_mask:0xf
	v_mov_b32_dpp v163, v161 quad_perm:[2,3,0,1] row_mask:0xf bank_mask:0xf
	v_cndmask_b32_e64 v156, v148, v162, s[20:21]
	v_cndmask_b32_e64 v157, v162, v150, s[20:21]
	v_cndmask_b32_e64 v158, v149, v163, s[20:21]
	v_cndmask_b32_e64 v159, v163, v151, s[20:21]
	v_cndmask_b32_e64 v160, v158, v156, s[24:25]
	v_cndmask_b32_e64 v161, v159, v157, s[24:25]
	s_nop 1
	v_mov_b32_dpp v162, v160 row_shl:4 row_mask:0xf bank_mask:0x5
	v_mov_b32_dpp v163, v161 row_shl:4 row_mask:0xf bank_mask:0x5
	v_mov_b32_dpp v162, v160 row_shr:4 row_mask:0xf bank_mask:0xa
	v_mov_b32_dpp v163, v161 row_shr:4 row_mask:0xf bank_mask:0xa
	v_cndmask_b32_e64 v208, v156, v162, s[24:25]
	v_cndmask_b32_e64 v209, v157, v163, s[24:25]
	v_cndmask_b32_e64 v210, v162, v158, s[24:25]
	v_cndmask_b32_e64 v211, v163, v159, s[24:25]
	global_store_dwordx4 v217, v[208:211], s[10:11] sc0 sc1
	s_add_u32 s10, s22, 0x88000
	s_addc_u32 s11, s23, 0
	v_cvt_pk_bf16_f32 v148, v54, v55
	v_cvt_pk_bf16_f32 v149, v56, v57
	v_cvt_pk_bf16_f32 v150, v50, v51
	v_cvt_pk_bf16_f32 v151, v52, v53
	s_nop 1
	v_mov_b32_dpp v152, v148 quad_perm:[1,0,3,2] row_mask:0xf bank_mask:0xf
	v_mov_b32_dpp v153, v149 quad_perm:[1,0,3,2] row_mask:0xf bank_mask:0xf
	v_mov_b32_dpp v154, v150 quad_perm:[1,0,3,2] row_mask:0xf bank_mask:0xf
	v_mov_b32_dpp v155, v151 quad_perm:[1,0,3,2] row_mask:0xf bank_mask:0xf
	v_perm_b32 v148, v152, v148, v216
	v_perm_b32 v149, v153, v149, v216
	v_perm_b32 v150, v154, v150, v216
	v_perm_b32 v151, v155, v151, v216
	v_cndmask_b32_e64 v160, v150, v148, s[20:21]
	v_cndmask_b32_e64 v161, v151, v149, s[20:21]
	s_nop 1
	v_mov_b32_dpp v162, v160 quad_perm:[2,3,0,1] row_mask:0xf bank_mask:0xf
	v_mov_b32_dpp v163, v161 quad_perm:[2,3,0,1] row_mask:0xf bank_mask:0xf
	v_cndmask_b32_e64 v156, v148, v162, s[20:21]
	v_cndmask_b32_e64 v157, v162, v150, s[20:21]
	v_cndmask_b32_e64 v158, v149, v163, s[20:21]
	v_cndmask_b32_e64 v159, v163, v151, s[20:21]
	v_cndmask_b32_e64 v160, v158, v156, s[24:25]
	v_cndmask_b32_e64 v161, v159, v157, s[24:25]
	s_nop 1
	v_mov_b32_dpp v162, v160 row_shl:4 row_mask:0xf bank_mask:0x5
	v_mov_b32_dpp v163, v161 row_shl:4 row_mask:0xf bank_mask:0x5
	v_mov_b32_dpp v162, v160 row_shr:4 row_mask:0xf bank_mask:0xa
	v_mov_b32_dpp v163, v161 row_shr:4 row_mask:0xf bank_mask:0xa
	v_cndmask_b32_e64 v212, v156, v162, s[24:25]
	v_cndmask_b32_e64 v213, v157, v163, s[24:25]
	v_cndmask_b32_e64 v214, v162, v158, s[24:25]
	v_cndmask_b32_e64 v215, v163, v159, s[24:25]
	global_store_dwordx4 v217, v[212:215], s[10:11] sc0 sc1
	s_add_u32 s10, s22, 0x9000
	s_addc_u32 s11, s23, 0
	v_cvt_pk_bf16_f32 v148, v46, v47
	v_cvt_pk_bf16_f32 v149, v48, v49
	v_cvt_pk_bf16_f32 v150, v42, v43
	v_cvt_pk_bf16_f32 v151, v44, v45
	s_nop 1
	v_mov_b32_dpp v152, v148 quad_perm:[1,0,3,2] row_mask:0xf bank_mask:0xf
	v_mov_b32_dpp v153, v149 quad_perm:[1,0,3,2] row_mask:0xf bank_mask:0xf
	v_mov_b32_dpp v154, v150 quad_perm:[1,0,3,2] row_mask:0xf bank_mask:0xf
	v_mov_b32_dpp v155, v151 quad_perm:[1,0,3,2] row_mask:0xf bank_mask:0xf
	v_perm_b32 v148, v152, v148, v216
	v_perm_b32 v149, v153, v149, v216
	v_perm_b32 v150, v154, v150, v216
	v_perm_b32 v151, v155, v151, v216
	v_cndmask_b32_e64 v160, v150, v148, s[20:21]
	v_cndmask_b32_e64 v161, v151, v149, s[20:21]
	s_nop 1
	v_mov_b32_dpp v162, v160 quad_perm:[2,3,0,1] row_mask:0xf bank_mask:0xf
	v_mov_b32_dpp v163, v161 quad_perm:[2,3,0,1] row_mask:0xf bank_mask:0xf
	v_cndmask_b32_e64 v156, v148, v162, s[20:21]
	v_cndmask_b32_e64 v157, v162, v150, s[20:21]
	v_cndmask_b32_e64 v158, v149, v163, s[20:21]
	v_cndmask_b32_e64 v159, v163, v151, s[20:21]
	v_cndmask_b32_e64 v160, v158, v156, s[24:25]
	v_cndmask_b32_e64 v161, v159, v157, s[24:25]
	s_nop 1
	v_mov_b32_dpp v162, v160 row_shl:4 row_mask:0xf bank_mask:0x5
	v_mov_b32_dpp v163, v161 row_shl:4 row_mask:0xf bank_mask:0x5
	v_mov_b32_dpp v162, v160 row_shr:4 row_mask:0xf bank_mask:0xa
	v_mov_b32_dpp v163, v161 row_shr:4 row_mask:0xf bank_mask:0xa
	v_cndmask_b32_e64 v208, v156, v162, s[24:25]
	v_cndmask_b32_e64 v209, v157, v163, s[24:25]
	v_cndmask_b32_e64 v210, v162, v158, s[24:25]
	v_cndmask_b32_e64 v211, v163, v159, s[24:25]
	global_store_dwordx4 v217, v[208:211], s[10:11] sc0 sc1
	s_add_u32 s10, s22, 0x89000
	s_addc_u32 s11, s23, 0
	v_cvt_pk_bf16_f32 v148, v38, v39
	v_cvt_pk_bf16_f32 v149, v40, v41
	v_cvt_pk_bf16_f32 v150, v34, v35
	v_cvt_pk_bf16_f32 v151, v36, v37
	s_nop 1
	v_mov_b32_dpp v152, v148 quad_perm:[1,0,3,2] row_mask:0xf bank_mask:0xf
	v_mov_b32_dpp v153, v149 quad_perm:[1,0,3,2] row_mask:0xf bank_mask:0xf
	v_mov_b32_dpp v154, v150 quad_perm:[1,0,3,2] row_mask:0xf bank_mask:0xf
	v_mov_b32_dpp v155, v151 quad_perm:[1,0,3,2] row_mask:0xf bank_mask:0xf
	v_perm_b32 v148, v152, v148, v216
	v_perm_b32 v149, v153, v149, v216
	v_perm_b32 v150, v154, v150, v216
	v_perm_b32 v151, v155, v151, v216
	v_cndmask_b32_e64 v160, v150, v148, s[20:21]
	v_cndmask_b32_e64 v161, v151, v149, s[20:21]
	s_nop 1
	v_mov_b32_dpp v162, v160 quad_perm:[2,3,0,1] row_mask:0xf bank_mask:0xf
	v_mov_b32_dpp v163, v161 quad_perm:[2,3,0,1] row_mask:0xf bank_mask:0xf
	v_cndmask_b32_e64 v156, v148, v162, s[20:21]
	v_cndmask_b32_e64 v157, v162, v150, s[20:21]
	v_cndmask_b32_e64 v158, v149, v163, s[20:21]
	v_cndmask_b32_e64 v159, v163, v151, s[20:21]
	v_cndmask_b32_e64 v160, v158, v156, s[24:25]
	v_cndmask_b32_e64 v161, v159, v157, s[24:25]
	s_nop 1
	v_mov_b32_dpp v162, v160 row_shl:4 row_mask:0xf bank_mask:0x5
	v_mov_b32_dpp v163, v161 row_shl:4 row_mask:0xf bank_mask:0x5
	v_mov_b32_dpp v162, v160 row_shr:4 row_mask:0xf bank_mask:0xa
	v_mov_b32_dpp v163, v161 row_shr:4 row_mask:0xf bank_mask:0xa
	v_cndmask_b32_e64 v212, v156, v162, s[24:25]
	v_cndmask_b32_e64 v213, v157, v163, s[24:25]
	v_cndmask_b32_e64 v214, v162, v158, s[24:25]
	v_cndmask_b32_e64 v215, v163, v159, s[24:25]
	global_store_dwordx4 v217, v[212:215], s[10:11] sc0 sc1
	s_add_u32 s10, s22, 0xa000
	s_addc_u32 s11, s23, 0
	v_cvt_pk_bf16_f32 v148, v28, v29
	v_cvt_pk_bf16_f32 v149, v30, v31
	v_cvt_pk_bf16_f32 v150, v24, v25
	v_cvt_pk_bf16_f32 v151, v26, v27
	s_nop 1
	v_mov_b32_dpp v152, v148 quad_perm:[1,0,3,2] row_mask:0xf bank_mask:0xf
	v_mov_b32_dpp v153, v149 quad_perm:[1,0,3,2] row_mask:0xf bank_mask:0xf
	v_mov_b32_dpp v154, v150 quad_perm:[1,0,3,2] row_mask:0xf bank_mask:0xf
	v_mov_b32_dpp v155, v151 quad_perm:[1,0,3,2] row_mask:0xf bank_mask:0xf
	v_perm_b32 v148, v152, v148, v216
	v_perm_b32 v149, v153, v149, v216
	v_perm_b32 v150, v154, v150, v216
	v_perm_b32 v151, v155, v151, v216
	v_cndmask_b32_e64 v160, v150, v148, s[20:21]
	v_cndmask_b32_e64 v161, v151, v149, s[20:21]
	s_nop 1
	v_mov_b32_dpp v162, v160 quad_perm:[2,3,0,1] row_mask:0xf bank_mask:0xf
	v_mov_b32_dpp v163, v161 quad_perm:[2,3,0,1] row_mask:0xf bank_mask:0xf
	v_cndmask_b32_e64 v156, v148, v162, s[20:21]
	v_cndmask_b32_e64 v157, v162, v150, s[20:21]
	v_cndmask_b32_e64 v158, v149, v163, s[20:21]
	v_cndmask_b32_e64 v159, v163, v151, s[20:21]
	v_cndmask_b32_e64 v160, v158, v156, s[24:25]
	v_cndmask_b32_e64 v161, v159, v157, s[24:25]
	s_nop 1
	v_mov_b32_dpp v162, v160 row_shl:4 row_mask:0xf bank_mask:0x5
	v_mov_b32_dpp v163, v161 row_shl:4 row_mask:0xf bank_mask:0x5
	v_mov_b32_dpp v162, v160 row_shr:4 row_mask:0xf bank_mask:0xa
	v_mov_b32_dpp v163, v161 row_shr:4 row_mask:0xf bank_mask:0xa
	v_cndmask_b32_e64 v208, v156, v162, s[24:25]
	v_cndmask_b32_e64 v209, v157, v163, s[24:25]
	v_cndmask_b32_e64 v210, v162, v158, s[24:25]
	v_cndmask_b32_e64 v211, v163, v159, s[24:25]
	global_store_dwordx4 v217, v[208:211], s[10:11] sc0 sc1
	s_add_u32 s10, s22, 0x8a000
	s_addc_u32 s11, s23, 0
	v_cvt_pk_bf16_f32 v148, v20, v21
	v_cvt_pk_bf16_f32 v149, v22, v23
	v_cvt_pk_bf16_f32 v150, v16, v17
	v_cvt_pk_bf16_f32 v151, v18, v19
	s_nop 1
	v_mov_b32_dpp v152, v148 quad_perm:[1,0,3,2] row_mask:0xf bank_mask:0xf
	v_mov_b32_dpp v153, v149 quad_perm:[1,0,3,2] row_mask:0xf bank_mask:0xf
	v_mov_b32_dpp v154, v150 quad_perm:[1,0,3,2] row_mask:0xf bank_mask:0xf
	v_mov_b32_dpp v155, v151 quad_perm:[1,0,3,2] row_mask:0xf bank_mask:0xf
	v_perm_b32 v148, v152, v148, v216
	v_perm_b32 v149, v153, v149, v216
	v_perm_b32 v150, v154, v150, v216
	v_perm_b32 v151, v155, v151, v216
	v_cndmask_b32_e64 v160, v150, v148, s[20:21]
	v_cndmask_b32_e64 v161, v151, v149, s[20:21]
	s_nop 1
	v_mov_b32_dpp v162, v160 quad_perm:[2,3,0,1] row_mask:0xf bank_mask:0xf
	v_mov_b32_dpp v163, v161 quad_perm:[2,3,0,1] row_mask:0xf bank_mask:0xf
	v_cndmask_b32_e64 v156, v148, v162, s[20:21]
	v_cndmask_b32_e64 v157, v162, v150, s[20:21]
	v_cndmask_b32_e64 v158, v149, v163, s[20:21]
	v_cndmask_b32_e64 v159, v163, v151, s[20:21]
	v_cndmask_b32_e64 v160, v158, v156, s[24:25]
	v_cndmask_b32_e64 v161, v159, v157, s[24:25]
	s_nop 1
	v_mov_b32_dpp v162, v160 row_shl:4 row_mask:0xf bank_mask:0x5
	v_mov_b32_dpp v163, v161 row_shl:4 row_mask:0xf bank_mask:0x5
	v_mov_b32_dpp v162, v160 row_shr:4 row_mask:0xf bank_mask:0xa
	v_mov_b32_dpp v163, v161 row_shr:4 row_mask:0xf bank_mask:0xa
	v_cndmask_b32_e64 v212, v156, v162, s[24:25]
	v_cndmask_b32_e64 v213, v157, v163, s[24:25]
	v_cndmask_b32_e64 v214, v162, v158, s[24:25]
	v_cndmask_b32_e64 v215, v163, v159, s[24:25]
	global_store_dwordx4 v217, v[212:215], s[10:11] sc0 sc1
	s_add_u32 s10, s22, 0xb000
	s_addc_u32 s11, s23, 0
	v_cvt_pk_bf16_f32 v148, v12, v13
	v_cvt_pk_bf16_f32 v149, v14, v15
	v_cvt_pk_bf16_f32 v150, v8, v9
	v_cvt_pk_bf16_f32 v151, v10, v11
	s_nop 1
	v_mov_b32_dpp v152, v148 quad_perm:[1,0,3,2] row_mask:0xf bank_mask:0xf
	v_mov_b32_dpp v153, v149 quad_perm:[1,0,3,2] row_mask:0xf bank_mask:0xf
	v_mov_b32_dpp v154, v150 quad_perm:[1,0,3,2] row_mask:0xf bank_mask:0xf
	v_mov_b32_dpp v155, v151 quad_perm:[1,0,3,2] row_mask:0xf bank_mask:0xf
	v_perm_b32 v148, v152, v148, v216
	v_perm_b32 v149, v153, v149, v216
	v_perm_b32 v150, v154, v150, v216
	v_perm_b32 v151, v155, v151, v216
	v_cndmask_b32_e64 v160, v150, v148, s[20:21]
	v_cndmask_b32_e64 v161, v151, v149, s[20:21]
	s_nop 1
	v_mov_b32_dpp v162, v160 quad_perm:[2,3,0,1] row_mask:0xf bank_mask:0xf
	v_mov_b32_dpp v163, v161 quad_perm:[2,3,0,1] row_mask:0xf bank_mask:0xf
	v_cndmask_b32_e64 v156, v148, v162, s[20:21]
	v_cndmask_b32_e64 v157, v162, v150, s[20:21]
	v_cndmask_b32_e64 v158, v149, v163, s[20:21]
	v_cndmask_b32_e64 v159, v163, v151, s[20:21]
	v_cndmask_b32_e64 v160, v158, v156, s[24:25]
	v_cndmask_b32_e64 v161, v159, v157, s[24:25]
	s_nop 1
	v_mov_b32_dpp v162, v160 row_shl:4 row_mask:0xf bank_mask:0x5
	v_mov_b32_dpp v163, v161 row_shl:4 row_mask:0xf bank_mask:0x5
	v_mov_b32_dpp v162, v160 row_shr:4 row_mask:0xf bank_mask:0xa
	v_mov_b32_dpp v163, v161 row_shr:4 row_mask:0xf bank_mask:0xa
	v_cndmask_b32_e64 v208, v156, v162, s[24:25]
	v_cndmask_b32_e64 v209, v157, v163, s[24:25]
	v_cndmask_b32_e64 v210, v162, v158, s[24:25]
	v_cndmask_b32_e64 v211, v163, v159, s[24:25]
	global_store_dwordx4 v217, v[208:211], s[10:11] sc0 sc1
	s_add_u32 s10, s22, 0x8b000
	s_addc_u32 s11, s23, 0
	v_cvt_pk_bf16_f32 v148, v4, v5
	v_cvt_pk_bf16_f32 v149, v6, v7
	v_cvt_pk_bf16_f32 v150, v0, v1
	v_cvt_pk_bf16_f32 v151, v2, v3
	s_nop 1
	v_mov_b32_dpp v152, v148 quad_perm:[1,0,3,2] row_mask:0xf bank_mask:0xf
	v_mov_b32_dpp v153, v149 quad_perm:[1,0,3,2] row_mask:0xf bank_mask:0xf
	v_mov_b32_dpp v154, v150 quad_perm:[1,0,3,2] row_mask:0xf bank_mask:0xf
	v_mov_b32_dpp v155, v151 quad_perm:[1,0,3,2] row_mask:0xf bank_mask:0xf
	v_perm_b32 v148, v152, v148, v216
	v_perm_b32 v149, v153, v149, v216
	v_perm_b32 v150, v154, v150, v216
	v_perm_b32 v151, v155, v151, v216
	v_cndmask_b32_e64 v160, v150, v148, s[20:21]
	v_cndmask_b32_e64 v161, v151, v149, s[20:21]
	s_nop 1
	v_mov_b32_dpp v162, v160 quad_perm:[2,3,0,1] row_mask:0xf bank_mask:0xf
	v_mov_b32_dpp v163, v161 quad_perm:[2,3,0,1] row_mask:0xf bank_mask:0xf
	v_cndmask_b32_e64 v156, v148, v162, s[20:21]
	v_cndmask_b32_e64 v157, v162, v150, s[20:21]
	v_cndmask_b32_e64 v158, v149, v163, s[20:21]
	v_cndmask_b32_e64 v159, v163, v151, s[20:21]
	v_cndmask_b32_e64 v160, v158, v156, s[24:25]
	v_cndmask_b32_e64 v161, v159, v157, s[24:25]
	s_nop 1
	v_mov_b32_dpp v162, v160 row_shl:4 row_mask:0xf bank_mask:0x5
	v_mov_b32_dpp v163, v161 row_shl:4 row_mask:0xf bank_mask:0x5
	v_mov_b32_dpp v162, v160 row_shr:4 row_mask:0xf bank_mask:0xa
	v_mov_b32_dpp v163, v161 row_shr:4 row_mask:0xf bank_mask:0xa
	v_cndmask_b32_e64 v212, v156, v162, s[24:25]
	v_cndmask_b32_e64 v213, v157, v163, s[24:25]
	v_cndmask_b32_e64 v214, v162, v158, s[24:25]
	v_cndmask_b32_e64 v215, v163, v159, s[24:25]
	global_store_dwordx4 v217, v[212:215], s[10:11] sc0 sc1
	s_branch .LBB0_364

.LBB0_416:
	s_lshl_b32 s15, s31, 8
	s_ashr_i32 s31, s30, 31
	s_add_i32 s15, s15, s45
	s_lshl_b64 s[10:11], s[30:31], 1
	s_add_u32 s26, s22, s10
	s_addc_u32 s27, s23, s11
	s_ashr_i32 s10, s15, 9
	s_and_b32 s10, s10, -4
	s_add_i32 s34, s30, s10
	s_lshr_b32 s10, s15, 2
	v_mov_b32_e32 v143, v33
	s_and_b32 s10, s10, 0x1f0
	v_lshl_add_u64 v[122:123], s[22:23], 0, v[142:143]
	v_mov_b32_e32 v145, v33
	v_or_b32_e32 v143, s10, v170
	s_and_b32 s10, s15, 0x7c0
	v_lshl_add_u64 v[126:127], v[122:123], 0, v[144:145]
	v_or_b32_e32 v122, s10, v166
	v_mov_b32_e32 v147, v33
	v_lshrrev_b32_e32 v145, 3, v122
	v_lshl_add_u64 v[148:149], s[22:23], 0, v[146:147]
	s_cmp_lt_i32 s13, 2
	s_mov_b64 s[10:11], -1
	s_cbranch_scc1 .LBB0_423
	s_cmp_gt_i32 s13, 3
	s_cbranch_scc0 .LBB0_419
	s_ashr_i32 s35, s34, 31
	s_lshl_b64 s[10:11], s[34:35], 19
	v_lshlrev_b32_e32 v128, 10, v143
	v_mov_b32_e32 v129, v33
	v_lshl_add_u64 v[150:151], v[148:149], 0, s[10:11]
	v_cvt_pk_bf16_f32 v122, v158, v159
	v_cvt_pk_bf16_f32 v123, v160, v161
	v_cvt_pk_bf16_f32 v124, v162, v163
	v_cvt_pk_bf16_f32 v125, v164, v165
	v_lshl_add_u64 v[128:129], v[150:151], 0, v[128:129]
	global_store_dwordx4 v[128:129], v[122:125], off sc0 sc1
	s_mov_b64 s[10:11], 0

.LBB0_423:
	v_or_b32_e32 v150, s15, v166
	v_lshlrev_b32_e32 v122, 8, v150
	v_lshl_add_u64 v[128:129], s[22:23], 0, v[32:33]
	v_and_b32_e32 v122, 0x7cf00, v122
	v_mov_b32_e32 v123, v33
	v_ashrrev_i32_e32 v151, 31, v150
	v_lshl_add_u64 v[156:157], v[128:129], 0, v[122:123]
	v_mul_lo_u32 v124, s20, v151
	v_mul_lo_u32 v125, s21, v150
	v_mad_u64_u32 v[122:123], s[36:37], s20, v150, 0
	v_add3_u32 v123, v123, v124, v125
	s_andn2_b64 vcc, exec, s[10:11]
	v_lshl_add_u64 v[154:155], v[122:123], 1, s[26:27]
	s_cbranch_vccnz .LBB0_428
	s_mov_b64 s[10:11], -1
	s_cmp_gt_i32 s13, 0
	v_cvt_pk_bf16_f32 v122, v158, v159
	v_cvt_pk_bf16_f32 v123, v160, v161
	v_cvt_pk_bf16_f32 v124, v162, v163
	v_cvt_pk_bf16_f32 v125, v164, v165
	s_cbranch_scc0 .LBB0_426
	s_ashr_i32 s35, s34, 31
	s_lshl_b64 s[10:11], s[34:35], 19
	v_lshl_add_u64 v[158:159], v[156:157], 0, s[10:11]
	global_store_dwordx4 v[158:159], v[122:125], off sc0 sc1
	s_mov_b64 s[10:11], 0
.LBB0_426:
	s_andn2_b64 vcc, exec, s[10:11]
	s_cbranch_vccnz .LBB0_428
	v_lshl_add_u64 v[158:159], v[154:155], 0, v[32:33]
	global_store_dwordx4 v[158:159], v[122:125], off sc0 sc1

.LBB0_442:
	s_cmp_gt_i32 s13, 3
	s_cbranch_scc0 .LBB0_444
	s_add_i32 s28, s34, 1
	s_ashr_i32 s29, s28, 31
	s_lshl_b64 s[28:29], s[28:29], 19
	v_lshlrev_b32_e32 v118, 10, v143
	v_mov_b32_e32 v119, v33
	v_lshl_add_u64 v[120:121], v[148:149], 0, s[28:29]
	v_cvt_pk_bf16_f32 v114, v122, v123
	v_cvt_pk_bf16_f32 v115, v124, v125
	v_cvt_pk_bf16_f32 v116, v158, v159
	v_cvt_pk_bf16_f32 v117, v160, v161
	v_lshl_add_u64 v[118:119], v[120:121], 0, v[118:119]
	global_store_dwordx4 v[118:119], v[114:117], off sc0 sc1
	s_mov_b64 s[28:29], 0

.LBB0_448:
	s_mov_b64 s[28:29], -1
	s_cmp_gt_i32 s13, 0
	v_cvt_pk_bf16_f32 v114, v122, v123
	v_cvt_pk_bf16_f32 v115, v124, v125
	v_cvt_pk_bf16_f32 v116, v158, v159
	v_cvt_pk_bf16_f32 v117, v160, v161
	s_cbranch_scc0 .LBB0_450
	s_add_i32 s28, s34, 1
	s_ashr_i32 s29, s28, 31
	s_lshl_b64 s[28:29], s[28:29], 19
	v_lshl_add_u64 v[118:119], v[156:157], 0, s[28:29]
	s_mov_b64 s[28:29], 0
	global_store_dwordx4 v[118:119], v[114:117], off sc0 sc1
.LBB0_450:
	s_andn2_b64 vcc, exec, s[28:29]
	s_cbranch_vccnz .LBB0_452
	v_lshl_add_u64 v[118:119], v[154:155], 0, v[32:33]
	global_store_dwordx4 v[118:119], v[114:117], off offset:256 sc0 sc1

.LBB0_469:
	s_lshr_b32 s31, s15, 3
	v_or_b32_e32 v110, 16, v150
	s_and_b32 s31, s31, 0xf8
	v_lshrrev_b32_e32 v106, 3, v110
	v_and_or_b32 v145, v106, 3, s31
	v_lshlrev_b32_e32 v106, 4, v110
	v_and_b32_e32 v106, 0x1f0, v106
	v_mov_b32_e32 v107, v33
	v_lshl_add_u64 v[114:115], s[22:23], 0, v[106:107]
	s_cmp_lt_i32 s13, 2
	s_mov_b64 s[36:37], -1
	s_cbranch_scc1 .LBB0_476
	s_cmp_gt_i32 s13, 3
	s_cbranch_scc0 .LBB0_472
	s_ashr_i32 s35, s34, 31
	s_lshl_b64 s[36:37], s[34:35], 19
	s_waitcnt lgkmcnt(0)
	v_lshlrev_b32_e32 v116, 10, v143
	v_mov_b32_e32 v117, v33
	v_lshl_add_u64 v[118:119], v[114:115], 0, s[36:37]
	v_cvt_pk_bf16_f32 v106, v120, v121
	v_cvt_pk_bf16_f32 v107, v122, v123
	v_cvt_pk_bf16_f32 v108, v124, v125
	v_cvt_pk_bf16_f32 v109, v152, v153
	v_lshl_add_u64 v[116:117], v[118:119], 0, v[116:117]
	global_store_dwordx4 v[116:117], v[106:109], off sc0 sc1
	s_mov_b64 s[36:37], 0

.LBB0_476:
	v_lshlrev_b32_e32 v106, 8, v110
	v_and_b32_e32 v106, 0x7df00, v106
	v_mov_b32_e32 v107, v33
	v_ashrrev_i32_e32 v111, 31, v110
	v_lshl_add_u64 v[118:119], v[128:129], 0, v[106:107]
	v_mul_lo_u32 v108, s20, v111
	v_mul_lo_u32 v109, s21, v110
	v_mad_u64_u32 v[106:107], s[52:53], s20, v110, 0
	v_add3_u32 v107, v107, v108, v109
	s_andn2_b64 vcc, exec, s[36:37]
	s_waitcnt lgkmcnt(0)
	v_lshl_add_u64 v[116:117], v[106:107], 1, s[26:27]
	s_cbranch_vccnz .LBB0_481
	s_mov_b64 s[36:37], -1
	s_cmp_gt_i32 s13, 0
	v_cvt_pk_bf16_f32 v106, v120, v121
	v_cvt_pk_bf16_f32 v107, v122, v123
	v_cvt_pk_bf16_f32 v108, v124, v125
	v_cvt_pk_bf16_f32 v109, v152, v153
	s_cbranch_scc0 .LBB0_479
	s_ashr_i32 s35, s34, 31
	s_lshl_b64 s[36:37], s[34:35], 19
	v_lshl_add_u64 v[120:121], v[118:119], 0, s[36:37]
	s_mov_b64 s[36:37], 0
	global_store_dwordx4 v[120:121], v[106:109], off sc0 sc1
.LBB0_479:
	s_andn2_b64 vcc, exec, s[36:37]
	s_cbranch_vccnz .LBB0_481
	v_lshl_add_u64 v[120:121], v[116:117], 0, v[32:33]
	global_store_dwordx4 v[120:121], v[106:109], off sc0 sc1

.LBB0_495:
	s_cmp_gt_i32 s13, 3
	s_cbranch_scc0 .LBB0_497
	s_add_i32 s36, s34, 1
	s_ashr_i32 s37, s36, 31
	s_lshl_b64 s[36:37], s[36:37], 19
	v_lshlrev_b32_e32 v102, 10, v143
	v_mov_b32_e32 v103, v33
	v_lshl_add_u64 v[104:105], v[114:115], 0, s[36:37]
	v_cvt_pk_bf16_f32 v98, v106, v107
	v_cvt_pk_bf16_f32 v99, v108, v109
	v_cvt_pk_bf16_f32 v100, v120, v121
	v_cvt_pk_bf16_f32 v101, v122, v123
	v_lshl_add_u64 v[102:103], v[104:105], 0, v[102:103]
	global_store_dwordx4 v[102:103], v[98:101], off sc0 sc1
	s_mov_b64 s[36:37], 0

.LBB0_501:
	s_mov_b64 s[36:37], -1
	s_cmp_gt_i32 s13, 0
	v_cvt_pk_bf16_f32 v98, v106, v107
	v_cvt_pk_bf16_f32 v99, v108, v109
	v_cvt_pk_bf16_f32 v100, v120, v121
	v_cvt_pk_bf16_f32 v101, v122, v123
	s_cbranch_scc0 .LBB0_503
	s_add_i32 s36, s34, 1
	s_ashr_i32 s37, s36, 31
	s_lshl_b64 s[36:37], s[36:37], 19
	v_lshl_add_u64 v[102:103], v[118:119], 0, s[36:37]
	s_mov_b64 s[36:37], 0
	global_store_dwordx4 v[102:103], v[98:101], off sc0 sc1
.LBB0_503:
	s_andn2_b64 vcc, exec, s[36:37]
	s_cbranch_vccnz .LBB0_505
	v_lshl_add_u64 v[102:103], v[116:117], 0, v[32:33]
	global_store_dwordx4 v[102:103], v[98:101], off offset:256 sc0 sc1

.LBB0_522:
	v_or_b32_e32 v94, 32, v150
	v_lshrrev_b32_e32 v90, 3, v94
	v_and_or_b32 v112, v90, 5, s31
	v_lshlrev_b32_e32 v90, 4, v94
	v_and_b32_e32 v90, 0x2f0, v90
	v_mov_b32_e32 v91, v33
	v_lshl_add_u64 v[98:99], s[22:23], 0, v[90:91]
	s_cmp_lt_i32 s13, 2
	s_mov_b64 s[36:37], -1
	s_cbranch_scc1 .LBB0_529
	s_cmp_gt_i32 s13, 3
	s_cbranch_scc0 .LBB0_525
	s_ashr_i32 s35, s34, 31
	s_lshl_b64 s[36:37], s[34:35], 19
	s_waitcnt lgkmcnt(0)
	v_lshlrev_b32_e32 v100, 10, v143
	v_mov_b32_e32 v101, v33
	v_lshl_add_u64 v[102:103], v[98:99], 0, s[36:37]
	v_cvt_pk_bf16_f32 v90, v104, v105
	v_cvt_pk_bf16_f32 v91, v106, v107
	v_cvt_pk_bf16_f32 v92, v108, v109
	v_cvt_pk_bf16_f32 v93, v110, v111
	v_lshl_add_u64 v[100:101], v[102:103], 0, v[100:101]
	global_store_dwordx4 v[100:101], v[90:93], off sc0 sc1
	s_mov_b64 s[36:37], 0

.LBB0_529:
	v_lshlrev_b32_e32 v90, 8, v94
	v_and_b32_e32 v90, 0x7ef00, v90
	v_mov_b32_e32 v91, v33
	v_ashrrev_i32_e32 v95, 31, v94
	v_lshl_add_u64 v[102:103], v[128:129], 0, v[90:91]
	v_mul_lo_u32 v92, s20, v95
	v_mul_lo_u32 v93, s21, v94
	v_mad_u64_u32 v[90:91], s[52:53], s20, v94, 0
	v_add3_u32 v91, v91, v92, v93
	s_andn2_b64 vcc, exec, s[36:37]
	s_waitcnt lgkmcnt(0)
	v_lshl_add_u64 v[100:101], v[90:91], 1, s[26:27]
	s_cbranch_vccnz .LBB0_534
	s_mov_b64 s[36:37], -1
	s_cmp_gt_i32 s13, 0
	v_cvt_pk_bf16_f32 v90, v104, v105
	v_cvt_pk_bf16_f32 v91, v106, v107
	v_cvt_pk_bf16_f32 v92, v108, v109
	v_cvt_pk_bf16_f32 v93, v110, v111
	s_cbranch_scc0 .LBB0_532
	s_ashr_i32 s35, s34, 31
	s_lshl_b64 s[36:37], s[34:35], 19
	v_lshl_add_u64 v[104:105], v[102:103], 0, s[36:37]
	s_mov_b64 s[36:37], 0
	global_store_dwordx4 v[104:105], v[90:93], off sc0 sc1
.LBB0_532:
	s_andn2_b64 vcc, exec, s[36:37]
	s_cbranch_vccnz .LBB0_534
	v_lshl_add_u64 v[104:105], v[100:101], 0, v[32:33]
	global_store_dwordx4 v[104:105], v[90:93], off sc0 sc1

.LBB0_548:
	s_cmp_gt_i32 s13, 3
	s_cbranch_scc0 .LBB0_550
	s_add_i32 s36, s34, 1
	s_ashr_i32 s37, s36, 31
	s_lshl_b64 s[36:37], s[36:37], 19
	v_lshlrev_b32_e32 v86, 10, v143
	v_mov_b32_e32 v87, v33
	v_lshl_add_u64 v[88:89], v[98:99], 0, s[36:37]
	v_cvt_pk_bf16_f32 v82, v90, v91
	v_cvt_pk_bf16_f32 v83, v92, v93
	v_cvt_pk_bf16_f32 v84, v104, v105
	v_cvt_pk_bf16_f32 v85, v106, v107
	v_lshl_add_u64 v[86:87], v[88:89], 0, v[86:87]
	global_store_dwordx4 v[86:87], v[82:85], off sc0 sc1
	s_mov_b64 s[36:37], 0

.LBB0_554:
	s_mov_b64 s[36:37], -1
	s_cmp_gt_i32 s13, 0
	v_cvt_pk_bf16_f32 v82, v90, v91
	v_cvt_pk_bf16_f32 v83, v92, v93
	v_cvt_pk_bf16_f32 v84, v104, v105
	v_cvt_pk_bf16_f32 v85, v106, v107
	s_cbranch_scc0 .LBB0_556
	s_add_i32 s36, s34, 1
	s_ashr_i32 s37, s36, 31
	s_lshl_b64 s[36:37], s[36:37], 19
	v_lshl_add_u64 v[86:87], v[102:103], 0, s[36:37]
	s_mov_b64 s[36:37], 0
	global_store_dwordx4 v[86:87], v[82:85], off sc0 sc1
.LBB0_556:
	s_andn2_b64 vcc, exec, s[36:37]
	s_cbranch_vccnz .LBB0_558
	v_lshl_add_u64 v[86:87], v[100:101], 0, v[32:33]
	global_store_dwordx4 v[86:87], v[82:85], off offset:256 sc0 sc1

.LBB0_575:
	v_or_b32_e32 v78, 48, v150
	v_lshrrev_b32_e32 v74, 3, v78
	v_and_or_b32 v96, v74, 7, s31
	v_lshlrev_b32_e32 v74, 4, v78
	v_and_b32_e32 v74, 0x3f0, v74
	v_mov_b32_e32 v75, v33
	v_lshl_add_u64 v[82:83], s[22:23], 0, v[74:75]
	s_cmp_lt_i32 s13, 2
	s_mov_b64 s[36:37], -1
	s_cbranch_scc1 .LBB0_582
	s_cmp_gt_i32 s13, 3
	s_cbranch_scc0 .LBB0_578
	s_ashr_i32 s35, s34, 31
	s_lshl_b64 s[36:37], s[34:35], 19
	s_waitcnt lgkmcnt(0)
	v_lshlrev_b32_e32 v84, 10, v143
	v_mov_b32_e32 v85, v33
	v_lshl_add_u64 v[86:87], v[82:83], 0, s[36:37]
	v_cvt_pk_bf16_f32 v74, v88, v89
	v_cvt_pk_bf16_f32 v75, v90, v91
	v_cvt_pk_bf16_f32 v76, v92, v93
	v_cvt_pk_bf16_f32 v77, v94, v95
	v_lshl_add_u64 v[84:85], v[86:87], 0, v[84:85]
	global_store_dwordx4 v[84:85], v[74:77], off sc0 sc1
	s_mov_b64 s[36:37], 0

.LBB0_582:
	v_lshlrev_b32_e32 v74, 8, v78
	v_and_b32_e32 v74, 0x7ff00, v74
	v_mov_b32_e32 v75, v33
	v_ashrrev_i32_e32 v79, 31, v78
	v_lshl_add_u64 v[86:87], v[128:129], 0, v[74:75]
	v_mul_lo_u32 v76, s20, v79
	v_mul_lo_u32 v77, s21, v78
	v_mad_u64_u32 v[74:75], s[52:53], s20, v78, 0
	v_add3_u32 v75, v75, v76, v77
	s_andn2_b64 vcc, exec, s[36:37]
	s_waitcnt lgkmcnt(0)
	v_lshl_add_u64 v[84:85], v[74:75], 1, s[26:27]
	s_cbranch_vccnz .LBB0_587
	s_mov_b64 s[36:37], -1
	s_cmp_gt_i32 s13, 0
	v_cvt_pk_bf16_f32 v74, v88, v89
	v_cvt_pk_bf16_f32 v75, v90, v91
	v_cvt_pk_bf16_f32 v76, v92, v93
	v_cvt_pk_bf16_f32 v77, v94, v95
	s_cbranch_scc0 .LBB0_585
	s_ashr_i32 s35, s34, 31
	s_lshl_b64 s[36:37], s[34:35], 19
	v_lshl_add_u64 v[88:89], v[86:87], 0, s[36:37]
	s_mov_b64 s[36:37], 0
	global_store_dwordx4 v[88:89], v[74:77], off sc0 sc1
.LBB0_585:
	s_andn2_b64 vcc, exec, s[36:37]
	s_cbranch_vccnz .LBB0_587
	v_lshl_add_u64 v[88:89], v[84:85], 0, v[32:33]
	global_store_dwordx4 v[88:89], v[74:77], off sc0 sc1

.LBB0_601:
	s_cmp_gt_i32 s13, 3
	s_cbranch_scc0 .LBB0_603
	s_add_i32 s36, s34, 1
	s_ashr_i32 s37, s36, 31
	s_lshl_b64 s[36:37], s[36:37], 19
	v_lshlrev_b32_e32 v70, 10, v143
	v_mov_b32_e32 v71, v33
	v_lshl_add_u64 v[72:73], v[82:83], 0, s[36:37]
	v_cvt_pk_bf16_f32 v66, v74, v75
	v_cvt_pk_bf16_f32 v67, v76, v77
	v_cvt_pk_bf16_f32 v68, v88, v89
	v_cvt_pk_bf16_f32 v69, v90, v91
	v_lshl_add_u64 v[70:71], v[72:73], 0, v[70:71]
	global_store_dwordx4 v[70:71], v[66:69], off sc0 sc1
	s_mov_b64 s[36:37], 0

.LBB0_607:
	s_mov_b64 s[36:37], -1
	s_cmp_gt_i32 s13, 0
	v_cvt_pk_bf16_f32 v66, v74, v75
	v_cvt_pk_bf16_f32 v67, v76, v77
	v_cvt_pk_bf16_f32 v68, v88, v89
	v_cvt_pk_bf16_f32 v69, v90, v91
	s_cbranch_scc0 .LBB0_609
	s_add_i32 s34, s34, 1
	s_ashr_i32 s35, s34, 31
	s_lshl_b64 s[34:35], s[34:35], 19
	v_lshl_add_u64 v[70:71], v[86:87], 0, s[34:35]
	s_mov_b64 s[36:37], 0
	global_store_dwordx4 v[70:71], v[66:69], off sc0 sc1
.LBB0_609:
	s_andn2_b64 vcc, exec, s[36:37]
	s_cbranch_vccnz .LBB0_611
	v_lshl_add_u64 v[70:71], v[84:85], 0, v[32:33]
	global_store_dwordx4 v[70:71], v[66:69], off offset:256 sc0 sc1

.LBB0_628:
	s_addk_i32 s15, 0x80
	s_ashr_i32 s31, s15, 9
	s_and_b32 s31, s31, -4
	s_add_i32 s30, s30, s31
	s_lshr_b32 s31, s15, 2
	s_and_b32 s31, s31, 0x1f0
	v_or_b32_e32 v78, s31, v170
	s_and_b32 s31, s15, 0x7c0
	v_or_b32_e32 v58, s31, v166
	v_lshrrev_b32_e32 v79, 3, v58
	s_cmp_lt_i32 s13, 2
	s_mov_b64 s[34:35], -1
	s_cbranch_scc1 .LBB0_635
	s_cmp_gt_i32 s13, 3
	s_cbranch_scc0 .LBB0_631
	s_ashr_i32 s31, s30, 31
	s_lshl_b64 s[34:35], s[30:31], 19
	v_lshlrev_b32_e32 v62, 10, v78
	v_mov_b32_e32 v63, v33
	v_lshl_add_u64 v[66:67], v[148:149], 0, s[34:35]
	v_cvt_pk_bf16_f32 v58, v70, v71
	v_cvt_pk_bf16_f32 v59, v72, v73
	v_cvt_pk_bf16_f32 v60, v74, v75
	v_cvt_pk_bf16_f32 v61, v76, v77
	v_lshl_add_u64 v[62:63], v[66:67], 0, v[62:63]
	global_store_dwordx4 v[62:63], v[58:61], off sc0 sc1
	s_mov_b64 s[34:35], 0

.LBB0_635:
	v_or_b32_e32 v62, s15, v166
	v_lshlrev_b32_e32 v58, 8, v62
	v_and_b32_e32 v58, 0x7cf00, v58
	v_mov_b32_e32 v59, v33
	v_ashrrev_i32_e32 v63, 31, v62
	s_waitcnt lgkmcnt(0)
	v_lshl_add_u64 v[68:69], v[128:129], 0, v[58:59]
	v_mul_lo_u32 v60, s20, v63
	v_mul_lo_u32 v61, s21, v62
	v_mad_u64_u32 v[58:59], s[36:37], s20, v62, 0
	v_add3_u32 v59, v59, v60, v61
	s_andn2_b64 vcc, exec, s[34:35]
	v_lshl_add_u64 v[66:67], v[58:59], 1, s[26:27]
	s_cbranch_vccnz .LBB0_640
	s_mov_b64 s[34:35], -1
	s_cmp_gt_i32 s13, 0
	v_cvt_pk_bf16_f32 v58, v70, v71
	v_cvt_pk_bf16_f32 v59, v72, v73
	v_cvt_pk_bf16_f32 v60, v74, v75
	v_cvt_pk_bf16_f32 v61, v76, v77
	s_cbranch_scc0 .LBB0_638
	s_ashr_i32 s31, s30, 31
	s_lshl_b64 s[34:35], s[30:31], 19
	v_lshl_add_u64 v[70:71], v[68:69], 0, s[34:35]
	s_mov_b64 s[34:35], 0
	global_store_dwordx4 v[70:71], v[58:61], off sc0 sc1
.LBB0_638:
	s_andn2_b64 vcc, exec, s[34:35]
	s_cbranch_vccnz .LBB0_640
	v_lshl_add_u64 v[70:71], v[66:67], 0, v[32:33]
	global_store_dwordx4 v[70:71], v[58:61], off sc0 sc1

.LBB0_654:
	s_cmp_gt_i32 s13, 3
	s_cbranch_scc0 .LBB0_656
	s_add_i32 s34, s30, 1
	s_ashr_i32 s35, s34, 31
	s_lshl_b64 s[34:35], s[34:35], 19
	v_lshlrev_b32_e32 v54, 10, v78
	v_mov_b32_e32 v55, v33
	v_lshl_add_u64 v[56:57], v[148:149], 0, s[34:35]
	v_cvt_pk_bf16_f32 v50, v58, v59
	v_cvt_pk_bf16_f32 v51, v60, v61
	v_cvt_pk_bf16_f32 v52, v70, v71
	v_cvt_pk_bf16_f32 v53, v72, v73
	v_lshl_add_u64 v[54:55], v[56:57], 0, v[54:55]
	global_store_dwordx4 v[54:55], v[50:53], off sc0 sc1
	s_mov_b64 s[34:35], 0

.LBB0_660:
	s_mov_b64 s[34:35], -1
	s_cmp_gt_i32 s13, 0
	v_cvt_pk_bf16_f32 v50, v58, v59
	v_cvt_pk_bf16_f32 v51, v60, v61
	v_cvt_pk_bf16_f32 v52, v70, v71
	v_cvt_pk_bf16_f32 v53, v72, v73
	s_cbranch_scc0 .LBB0_662
	s_add_i32 s34, s30, 1
	s_ashr_i32 s35, s34, 31
	s_lshl_b64 s[34:35], s[34:35], 19
	v_lshl_add_u64 v[54:55], v[68:69], 0, s[34:35]
	s_mov_b64 s[34:35], 0
	global_store_dwordx4 v[54:55], v[50:53], off sc0 sc1
.LBB0_662:
	s_andn2_b64 vcc, exec, s[34:35]
	s_cbranch_vccnz .LBB0_664
	v_lshl_add_u64 v[54:55], v[66:67], 0, v[32:33]
	global_store_dwordx4 v[54:55], v[50:53], off offset:256 sc0 sc1

.LBB0_681:
	s_lshr_b32 s15, s15, 3
	v_or_b32_e32 v46, 16, v62
	s_and_b32 s15, s15, 0xf8
	v_lshrrev_b32_e32 v42, 3, v46
	v_and_or_b32 v63, v42, 7, s15
	v_lshlrev_b32_e32 v42, 4, v46
	v_and_b32_e32 v42, 0x3f0, v42
	v_mov_b32_e32 v43, v33
	v_lshl_add_u64 v[50:51], s[22:23], 0, v[42:43]
	s_cmp_lt_i32 s13, 2
	s_mov_b64 s[34:35], -1
	s_cbranch_scc1 .LBB0_688
	s_cmp_gt_i32 s13, 3
	s_cbranch_scc0 .LBB0_684
	s_ashr_i32 s31, s30, 31
	s_lshl_b64 s[34:35], s[30:31], 19
	s_waitcnt lgkmcnt(0)
	v_lshlrev_b32_e32 v52, 10, v78
	v_mov_b32_e32 v53, v33
	v_lshl_add_u64 v[54:55], v[50:51], 0, s[34:35]
	v_cvt_pk_bf16_f32 v42, v56, v57
	v_cvt_pk_bf16_f32 v43, v58, v59
	v_cvt_pk_bf16_f32 v44, v60, v61
	v_cvt_pk_bf16_f32 v45, v64, v65
	v_lshl_add_u64 v[52:53], v[54:55], 0, v[52:53]
	global_store_dwordx4 v[52:53], v[42:45], off sc0 sc1
	s_mov_b64 s[34:35], 0

.LBB0_688:
	v_lshlrev_b32_e32 v42, 8, v46
	v_and_b32_e32 v42, 0x7ff00, v42
	v_mov_b32_e32 v43, v33
	v_ashrrev_i32_e32 v47, 31, v46
	v_lshl_add_u64 v[54:55], v[128:129], 0, v[42:43]
	v_mul_lo_u32 v44, s20, v47
	v_mul_lo_u32 v45, s21, v46
	v_mad_u64_u32 v[42:43], s[36:37], s20, v46, 0
	v_add3_u32 v43, v43, v44, v45
	s_andn2_b64 vcc, exec, s[34:35]
	s_waitcnt lgkmcnt(0)
	v_lshl_add_u64 v[52:53], v[42:43], 1, s[26:27]
	s_cbranch_vccnz .LBB0_693
	s_mov_b64 s[34:35], -1
	s_cmp_gt_i32 s13, 0
	v_cvt_pk_bf16_f32 v42, v56, v57
	v_cvt_pk_bf16_f32 v43, v58, v59
	v_cvt_pk_bf16_f32 v44, v60, v61
	v_cvt_pk_bf16_f32 v45, v64, v65
	s_cbranch_scc0 .LBB0_691
	s_ashr_i32 s31, s30, 31
	s_lshl_b64 s[34:35], s[30:31], 19
	v_lshl_add_u64 v[56:57], v[54:55], 0, s[34:35]
	s_mov_b64 s[34:35], 0
	global_store_dwordx4 v[56:57], v[42:45], off sc0 sc1
.LBB0_691:
	s_andn2_b64 vcc, exec, s[34:35]
	s_cbranch_vccnz .LBB0_693
	v_lshl_add_u64 v[56:57], v[52:53], 0, v[32:33]
	global_store_dwordx4 v[56:57], v[42:45], off sc0 sc1

.LBB0_707:
	s_cmp_gt_i32 s13, 3
	s_cbranch_scc0 .LBB0_709
	s_add_i32 s34, s30, 1
	s_ashr_i32 s35, s34, 31
	s_lshl_b64 s[34:35], s[34:35], 19
	v_lshlrev_b32_e32 v38, 10, v78
	v_mov_b32_e32 v39, v33
	v_lshl_add_u64 v[40:41], v[50:51], 0, s[34:35]
	v_cvt_pk_bf16_f32 v34, v42, v43
	v_cvt_pk_bf16_f32 v35, v44, v45
	v_cvt_pk_bf16_f32 v36, v56, v57
	v_cvt_pk_bf16_f32 v37, v58, v59
	v_lshl_add_u64 v[38:39], v[40:41], 0, v[38:39]
	global_store_dwordx4 v[38:39], v[34:37], off sc0 sc1
	s_mov_b64 s[34:35], 0

.LBB0_713:
	s_mov_b64 s[34:35], -1
	s_cmp_gt_i32 s13, 0
	v_cvt_pk_bf16_f32 v34, v42, v43
	v_cvt_pk_bf16_f32 v35, v44, v45
	v_cvt_pk_bf16_f32 v36, v56, v57
	v_cvt_pk_bf16_f32 v37, v58, v59
	s_cbranch_scc0 .LBB0_715
	s_add_i32 s34, s30, 1
	s_ashr_i32 s35, s34, 31
	s_lshl_b64 s[34:35], s[34:35], 19
	v_lshl_add_u64 v[38:39], v[54:55], 0, s[34:35]
	s_mov_b64 s[34:35], 0
	global_store_dwordx4 v[38:39], v[34:37], off sc0 sc1
.LBB0_715:
	s_andn2_b64 vcc, exec, s[34:35]
	s_cbranch_vccnz .LBB0_717
	v_lshl_add_u64 v[38:39], v[52:53], 0, v[32:33]
	global_store_dwordx4 v[38:39], v[34:37], off offset:256 sc0 sc1

.LBB0_734:
	v_or_b32_e32 v28, 32, v62
	v_lshrrev_b32_e32 v24, 3, v28
	v_and_or_b32 v48, v24, 7, s15
	v_lshlrev_b32_e32 v24, 4, v28
	v_and_b32_e32 v24, 0x3f0, v24
	v_mov_b32_e32 v25, v33
	v_lshl_add_u64 v[34:35], s[22:23], 0, v[24:25]
	s_cmp_lt_i32 s13, 2
	s_mov_b64 s[34:35], -1
	s_cbranch_scc1 .LBB0_741
	s_cmp_gt_i32 s13, 3
	s_cbranch_scc0 .LBB0_737
	s_ashr_i32 s31, s30, 31
	s_lshl_b64 s[34:35], s[30:31], 19
	s_waitcnt lgkmcnt(0)
	v_lshlrev_b32_e32 v36, 10, v78
	v_mov_b32_e32 v37, v33
	v_lshl_add_u64 v[38:39], v[34:35], 0, s[34:35]
	v_cvt_pk_bf16_f32 v24, v40, v41
	v_cvt_pk_bf16_f32 v25, v42, v43
	v_cvt_pk_bf16_f32 v26, v44, v45
	v_cvt_pk_bf16_f32 v27, v46, v47
	v_lshl_add_u64 v[36:37], v[38:39], 0, v[36:37]
	global_store_dwordx4 v[36:37], v[24:27], off sc0 sc1
	s_mov_b64 s[34:35], 0

.LBB0_741:
	v_lshlrev_b32_e32 v24, 8, v28
	v_and_b32_e32 v24, 0x7ff00, v24
	v_mov_b32_e32 v25, v33
	v_ashrrev_i32_e32 v29, 31, v28
	v_lshl_add_u64 v[38:39], v[128:129], 0, v[24:25]
	v_mul_lo_u32 v26, s20, v29
	v_mul_lo_u32 v27, s21, v28
	v_mad_u64_u32 v[24:25], s[36:37], s20, v28, 0
	v_add3_u32 v25, v25, v26, v27
	s_andn2_b64 vcc, exec, s[34:35]
	s_waitcnt lgkmcnt(0)
	v_lshl_add_u64 v[36:37], v[24:25], 1, s[26:27]
	s_cbranch_vccnz .LBB0_746
	s_mov_b64 s[34:35], -1
	s_cmp_gt_i32 s13, 0
	v_cvt_pk_bf16_f32 v24, v40, v41
	v_cvt_pk_bf16_f32 v25, v42, v43
	v_cvt_pk_bf16_f32 v26, v44, v45
	v_cvt_pk_bf16_f32 v27, v46, v47
	s_cbranch_scc0 .LBB0_744
	s_ashr_i32 s31, s30, 31
	s_lshl_b64 s[34:35], s[30:31], 19
	v_lshl_add_u64 v[40:41], v[38:39], 0, s[34:35]
	s_mov_b64 s[34:35], 0
	global_store_dwordx4 v[40:41], v[24:27], off sc0 sc1
.LBB0_744:
	s_andn2_b64 vcc, exec, s[34:35]
	s_cbranch_vccnz .LBB0_746
	v_lshl_add_u64 v[40:41], v[36:37], 0, v[32:33]
	global_store_dwordx4 v[40:41], v[24:27], off sc0 sc1

.LBB0_760:
	s_cmp_gt_i32 s13, 3
	s_cbranch_scc0 .LBB0_762
	s_add_i32 s34, s30, 1
	s_ashr_i32 s35, s34, 31
	s_lshl_b64 s[34:35], s[34:35], 19
	v_lshlrev_b32_e32 v20, 10, v78
	v_mov_b32_e32 v21, v33
	v_lshl_add_u64 v[22:23], v[34:35], 0, s[34:35]
	v_cvt_pk_bf16_f32 v16, v24, v25
	v_cvt_pk_bf16_f32 v17, v26, v27
	v_cvt_pk_bf16_f32 v18, v40, v41
	v_cvt_pk_bf16_f32 v19, v42, v43
	v_lshl_add_u64 v[20:21], v[22:23], 0, v[20:21]
	global_store_dwordx4 v[20:21], v[16:19], off sc0 sc1
	s_mov_b64 s[34:35], 0

.LBB0_766:
	s_mov_b64 s[34:35], -1
	s_cmp_gt_i32 s13, 0
	v_cvt_pk_bf16_f32 v16, v24, v25
	v_cvt_pk_bf16_f32 v17, v26, v27
	v_cvt_pk_bf16_f32 v18, v40, v41
	v_cvt_pk_bf16_f32 v19, v42, v43
	s_cbranch_scc0 .LBB0_768
	s_add_i32 s34, s30, 1
	s_ashr_i32 s35, s34, 31
	s_lshl_b64 s[34:35], s[34:35], 19
	v_lshl_add_u64 v[20:21], v[38:39], 0, s[34:35]
	s_mov_b64 s[34:35], 0
	global_store_dwordx4 v[20:21], v[16:19], off sc0 sc1
.LBB0_768:
	s_andn2_b64 vcc, exec, s[34:35]
	s_cbranch_vccnz .LBB0_770
	v_lshl_add_u64 v[20:21], v[36:37], 0, v[32:33]
	global_store_dwordx4 v[20:21], v[16:19], off offset:256 sc0 sc1

.LBB0_787:
	v_or_b32_e32 v12, 48, v62
	v_lshrrev_b32_e32 v8, 3, v12
	v_and_or_b32 v30, v8, 7, s15
	v_lshlrev_b32_e32 v8, 4, v12
	v_and_b32_e32 v8, 0x3f0, v8
	v_mov_b32_e32 v9, v33
	v_lshl_add_u64 v[16:17], s[22:23], 0, v[8:9]
	s_cmp_lt_i32 s13, 2
	s_mov_b64 s[22:23], -1
	s_cbranch_scc1 .LBB0_794
	s_cmp_gt_i32 s13, 3
	s_cbranch_scc0 .LBB0_790
	s_ashr_i32 s31, s30, 31
	s_lshl_b64 s[22:23], s[30:31], 19
	s_waitcnt lgkmcnt(0)
	v_lshlrev_b32_e32 v18, 10, v78
	v_mov_b32_e32 v19, v33
	v_lshl_add_u64 v[20:21], v[16:17], 0, s[22:23]
	v_cvt_pk_bf16_f32 v8, v22, v23
	v_cvt_pk_bf16_f32 v9, v24, v25
	v_cvt_pk_bf16_f32 v10, v26, v27
	v_cvt_pk_bf16_f32 v11, v28, v29
	v_lshl_add_u64 v[18:19], v[20:21], 0, v[18:19]
	global_store_dwordx4 v[18:19], v[8:11], off sc0 sc1
	s_mov_b64 s[22:23], 0

.LBB0_794:
	v_lshlrev_b32_e32 v8, 8, v12
	v_and_b32_e32 v8, 0x7ff00, v8
	v_mov_b32_e32 v9, v33
	v_ashrrev_i32_e32 v13, 31, v12
	v_lshl_add_u64 v[20:21], v[128:129], 0, v[8:9]
	v_mul_lo_u32 v10, s20, v13
	v_mul_lo_u32 v11, s21, v12
	v_mad_u64_u32 v[8:9], s[20:21], s20, v12, 0
	v_add3_u32 v9, v9, v10, v11
	s_andn2_b64 vcc, exec, s[22:23]
	s_waitcnt lgkmcnt(0)
	v_lshl_add_u64 v[18:19], v[8:9], 1, s[26:27]
	s_cbranch_vccnz .LBB0_799
	s_mov_b64 s[20:21], -1
	s_cmp_gt_i32 s13, 0
	v_cvt_pk_bf16_f32 v8, v22, v23
	v_cvt_pk_bf16_f32 v9, v24, v25
	v_cvt_pk_bf16_f32 v10, v26, v27
	v_cvt_pk_bf16_f32 v11, v28, v29
	s_cbranch_scc0 .LBB0_797
	s_ashr_i32 s31, s30, 31
	s_lshl_b64 s[20:21], s[30:31], 19
	v_lshl_add_u64 v[22:23], v[20:21], 0, s[20:21]
	s_mov_b64 s[20:21], 0
	global_store_dwordx4 v[22:23], v[8:11], off sc0 sc1
.LBB0_797:
	s_andn2_b64 vcc, exec, s[20:21]
	s_cbranch_vccnz .LBB0_799
	v_lshl_add_u64 v[22:23], v[18:19], 0, v[32:33]
	global_store_dwordx4 v[22:23], v[8:11], off sc0 sc1

.LBB0_813:
	s_cmp_gt_i32 s13, 3
	s_cbranch_scc0 .LBB0_815
	s_add_i32 s8, s30, 1
	s_ashr_i32 s9, s8, 31
	s_lshl_b64 s[8:9], s[8:9], 19
	v_lshlrev_b32_e32 v4, 10, v78
	v_mov_b32_e32 v5, v33
	v_lshl_add_u64 v[6:7], v[16:17], 0, s[8:9]
	v_cvt_pk_bf16_f32 v0, v8, v9
	v_cvt_pk_bf16_f32 v1, v10, v11
	v_cvt_pk_bf16_f32 v2, v22, v23
	v_cvt_pk_bf16_f32 v3, v24, v25
	v_lshl_add_u64 v[4:5], v[6:7], 0, v[4:5]
	global_store_dwordx4 v[4:5], v[0:3], off sc0 sc1
	s_mov_b64 s[8:9], 0

.LBB0_819:
	s_mov_b64 s[8:9], -1
	s_cmp_gt_i32 s13, 0
	v_cvt_pk_bf16_f32 v0, v8, v9
	v_cvt_pk_bf16_f32 v1, v10, v11
	v_cvt_pk_bf16_f32 v2, v22, v23
	v_cvt_pk_bf16_f32 v3, v24, v25
	s_cbranch_scc0 .LBB0_821
	s_add_i32 s8, s30, 1
	s_ashr_i32 s9, s8, 31
	s_lshl_b64 s[8:9], s[8:9], 19
	v_lshl_add_u64 v[4:5], v[20:21], 0, s[8:9]
	s_mov_b64 s[8:9], 0
	global_store_dwordx4 v[4:5], v[0:3], off sc0 sc1
.LBB0_821:
	s_andn2_b64 vcc, exec, s[8:9]
	s_cbranch_vccnz .LBB0_823
	v_lshl_add_u64 v[4:5], v[18:19], 0, v[32:33]
	global_store_dwordx4 v[4:5], v[0:3], off offset:256 sc0 sc1
